# barrier: each workgroup issues its acquire invalidate at arrival time instead of after the release
# speedup vs baseline: 1.0365x; 1.0073x over previous
; __device__ __forceinline__ unsigned xb_ld(unsigned* p)              { return __hip_atomic_load(p, __ATOMIC_RELAXED, __HIP_MEMORY_SCOPE_AGENT); }
; __device__ __forceinline__ unsigned xb_add(unsigned* p, unsigned v) { return __hip_atomic_fetch_add(p, v, __ATOMIC_RELAXED, __HIP_MEMORY_SCOPE_AGENT); }
; #define XB_SPIN(cond, bar) do { unsigned _sp = 0; while (cond) { __builtin_amdgcn_s_sleep(1); \
;     if ((++_sp & 255u) == 0u) { if (xb_ld(&(bar)[XB_TMO])) break; if (_sp > XB_SPIN_CAP) { atomicAdd(&(bar)[XB_TMO], 1u); break; } } } } while (0)
; __device__ __forceinline__ void xcd_barrier(const XcdBarrier& b) {
;     ...
;         unsigned nloc = b.st[0], nx = b.st[1];
;         if (nloc == 0u) { xcd_barrier_complete(bar, b.x, nloc, nx); b.st[0] = nloc; b.st[1] = nx; }
;         const unsigned old = xb_add(&bar[XB_XSUB(b.x)], 1u);
;         const unsigned gen = old / nloc;
;         if (old + 1u == (gen + 1u) * nloc) {
;             __builtin_amdgcn_fence(__ATOMIC_RELEASE, "agent");
;             asm volatile("s_waitcnt vmcnt(0)" ::: "memory");
;             const unsigned og = xb_add(&bar[XB_TOP], 1u);
;             const unsigned tg = og / nx;
;             if (og + 1u == (tg + 1u) * nx) xb_add(&bar[XB_TOPGEN], 1u);
;             else XB_SPIN(xb_ld(&bar[XB_TOPGEN]) == tg, bar);
;             __builtin_amdgcn_fence(__ATOMIC_ACQUIRE, "agent");
;             xb_add(&bar[XB_XGEN(b.x)], 1u);
;             asm volatile("s_waitcnt vmcnt(0)" ::: "memory");
;         } else {
;             XB_SPIN(xb_ld(&bar[XB_XGEN(b.x)]) == gen, bar);
;             __builtin_amdgcn_fence(__ATOMIC_ACQUIRE, "agent");
;             asm volatile("s_waitcnt vmcnt(0)" ::: "memory");
.LBB0_140:
	s_or_b64 exec, exec, s[10:11]
	v_cvt_f32_u32_e32 v4, v2
	s_waitcnt vmcnt(0)
	buffer_inv sc1
	v_readfirstlane_b32 s3, v3
	v_sub_u32_e32 v3, 0, v2
	v_rcp_iflag_f32_e32 v4, v4
	v_add_u32_e32 v5, s3, v1
	v_mul_f32_e32 v4, 0x4f7ffffe, v4
	v_cvt_u32_f32_e32 v4, v4
	v_mul_lo_u32 v1, v3, v4
	v_mul_hi_u32 v1, v4, v1
	v_add_u32_e32 v1, v4, v1
	v_mul_hi_u32 v1, v5, v1
	v_mul_lo_u32 v3, v1, v2
	v_sub_u32_e32 v3, v5, v3
	v_add_u32_e32 v4, 1, v1
	v_cmp_ge_u32_e32 vcc, v3, v2
	s_nop 1
	v_cndmask_b32_e32 v1, v1, v4, vcc
	v_sub_u32_e32 v4, v3, v2
	v_cndmask_b32_e32 v3, v3, v4, vcc
	v_add_u32_e32 v4, 1, v1
	v_cmp_ge_u32_e32 vcc, v3, v2
	v_add_u32_e32 v3, 1, v5
	s_nop 0
	v_cndmask_b32_e32 v1, v1, v4, vcc
	v_mul_lo_u32 v4, v2, v1
	v_add_u32_e32 v2, v4, v2
	v_cmp_ne_u32_e32 vcc, v3, v2
	s_and_saveexec_b64 s[8:9], vcc
	s_xor_b64 s[8:9], exec, s[8:9]
	s_cbranch_execz .LBB0_154
	s_waitcnt lgkmcnt(0)
	v_mov_b32_e32 v0, 0x83100
	global_load_dword v0, v0, s[30:31] offset:1024 sc1
	s_add_u32 s14, s30, 0x83500
	s_addc_u32 s15, s31, 0
	s_waitcnt vmcnt(0)
	v_cmp_eq_u32_e32 vcc, v0, v1
	s_and_saveexec_b64 s[10:11], vcc
	s_cbranch_execz .LBB0_153
	s_add_u32 s12, s30, 0x80200
	s_addc_u32 s13, s31, 0
	s_mov_b32 s3, 1
	s_mov_b64 s[16:17], 0
	v_mov_b32_e32 v0, 0
	s_branch .LBB0_144

; __device__ __forceinline__ unsigned xb_ld(unsigned* p)              { return __hip_atomic_load(p, __ATOMIC_RELAXED, __HIP_MEMORY_SCOPE_AGENT); }
; #define XB_SPIN(cond, bar) do { unsigned _sp = 0; while (cond) { __builtin_amdgcn_s_sleep(1); \
;     if ((++_sp & 255u) == 0u) { if (xb_ld(&(bar)[XB_TMO])) break; if (_sp > XB_SPIN_CAP) { atomicAdd(&(bar)[XB_TMO], 1u); break; } } } } while (0)
; __device__ __forceinline__ void xcd_barrier(const XcdBarrier& b) {
;     ...
;         } else {
;             XB_SPIN(xb_ld(&bar[XB_XGEN(b.x)]) == gen, bar);
;             __builtin_amdgcn_fence(__ATOMIC_ACQUIRE, "agent");
;             asm volatile("s_waitcnt vmcnt(0)" ::: "memory");
.LBB0_153:
	s_or_b64 exec, exec, s[10:11]
	s_waitcnt vmcnt(0)
	s_waitcnt vmcnt(0)

; __device__ __forceinline__ unsigned xb_ld(unsigned* p)              { return __hip_atomic_load(p, __ATOMIC_RELAXED, __HIP_MEMORY_SCOPE_AGENT); }
; __device__ __forceinline__ unsigned xb_add(unsigned* p, unsigned v) { return __hip_atomic_fetch_add(p, v, __ATOMIC_RELAXED, __HIP_MEMORY_SCOPE_AGENT); }
; #define XB_SPIN(cond, bar) do { unsigned _sp = 0; while (cond) { __builtin_amdgcn_s_sleep(1); \
;     if ((++_sp & 255u) == 0u) { if (xb_ld(&(bar)[XB_TMO])) break; if (_sp > XB_SPIN_CAP) { atomicAdd(&(bar)[XB_TMO], 1u); break; } } } } while (0)
; __device__ __forceinline__ void xcd_barrier(const XcdBarrier& b) {
;     ...
;             const unsigned og = xb_add(&bar[XB_TOP], 1u);
;             const unsigned tg = og / nx;
;             if (og + 1u == (tg + 1u) * nx) xb_add(&bar[XB_TOPGEN], 1u);
;             else XB_SPIN(xb_ld(&bar[XB_TOPGEN]) == tg, bar);
;             __builtin_amdgcn_fence(__ATOMIC_ACQUIRE, "agent");
;             xb_add(&bar[XB_XGEN(b.x)], 1u);
;             asm volatile("s_waitcnt vmcnt(0)" ::: "memory");
.LBB0_171:
	s_or_b64 exec, exec, s[8:9]
	s_mov_b64 s[8:9], exec
	v_mbcnt_lo_u32_b32 v0, s8, 0
	v_mbcnt_hi_u32_b32 v0, s9, v0
	v_cmp_eq_u32_e32 vcc, 0, v0
	s_waitcnt vmcnt(0)
	s_and_saveexec_b64 s[10:11], vcc
	s_cbranch_execz .LBB0_173
	s_bcnt1_i32_b64 s3, s[8:9]
	v_mov_b32_e32 v0, 0x2000
	v_mov_b32_e32 v1, s3
	global_atomic_add v0, v1, s[6:7] offset:1024

; __device__ __forceinline__ unsigned xb_ld(unsigned* p)              { return __hip_atomic_load(p, __ATOMIC_RELAXED, __HIP_MEMORY_SCOPE_AGENT); }
; __device__ __forceinline__ unsigned xb_add(unsigned* p, unsigned v) { return __hip_atomic_fetch_add(p, v, __ATOMIC_RELAXED, __HIP_MEMORY_SCOPE_AGENT); }
; #define XB_SPIN(cond, bar) do { unsigned _sp = 0; while (cond) { __builtin_amdgcn_s_sleep(1); \
;     if ((++_sp & 255u) == 0u) { if (xb_ld(&(bar)[XB_TMO])) break; if (_sp > XB_SPIN_CAP) { atomicAdd(&(bar)[XB_TMO], 1u); break; } } } } while (0)
; __device__ __forceinline__ void xcd_barrier(const XcdBarrier& b) {
;     ...
;         unsigned nloc = b.st[0], nx = b.st[1];
;         if (nloc == 0u) { xcd_barrier_complete(bar, b.x, nloc, nx); b.st[0] = nloc; b.st[1] = nx; }
;         const unsigned old = xb_add(&bar[XB_XSUB(b.x)], 1u);
;         const unsigned gen = old / nloc;
;         if (old + 1u == (gen + 1u) * nloc) {
;             __builtin_amdgcn_fence(__ATOMIC_RELEASE, "agent");
;             asm volatile("s_waitcnt vmcnt(0)" ::: "memory");
;             const unsigned og = xb_add(&bar[XB_TOP], 1u);
;             const unsigned tg = og / nx;
;             if (og + 1u == (tg + 1u) * nx) xb_add(&bar[XB_TOPGEN], 1u);
;             else XB_SPIN(xb_ld(&bar[XB_TOPGEN]) == tg, bar);
;             __builtin_amdgcn_fence(__ATOMIC_ACQUIRE, "agent");
;             xb_add(&bar[XB_XGEN(b.x)], 1u);
;             asm volatile("s_waitcnt vmcnt(0)" ::: "memory");
;         } else {
;             XB_SPIN(xb_ld(&bar[XB_XGEN(b.x)]) == gen, bar);
;             __builtin_amdgcn_fence(__ATOMIC_ACQUIRE, "agent");
;             asm volatile("s_waitcnt vmcnt(0)" ::: "memory");
.LBB0_669:
	s_or_b64 exec, exec, s[8:9]
	v_cvt_f32_u32_e32 v4, v2
	s_waitcnt vmcnt(0)
	buffer_inv sc1
	v_readfirstlane_b32 s3, v3
	v_sub_u32_e32 v3, 0, v2
	v_rcp_iflag_f32_e32 v4, v4
	v_add_u32_e32 v5, s3, v1
	v_mul_f32_e32 v4, 0x4f7ffffe, v4
	v_cvt_u32_f32_e32 v4, v4
	v_mul_lo_u32 v1, v3, v4
	v_mul_hi_u32 v1, v4, v1
	v_add_u32_e32 v1, v4, v1
	v_mul_hi_u32 v1, v5, v1
	v_mul_lo_u32 v3, v1, v2
	v_sub_u32_e32 v3, v5, v3
	v_add_u32_e32 v4, 1, v1
	v_cmp_ge_u32_e32 vcc, v3, v2
	s_nop 1
	v_cndmask_b32_e32 v1, v1, v4, vcc
	v_sub_u32_e32 v4, v3, v2
	v_cndmask_b32_e32 v3, v3, v4, vcc
	v_add_u32_e32 v4, 1, v1
	v_cmp_ge_u32_e32 vcc, v3, v2
	v_add_u32_e32 v3, 1, v5
	s_nop 0
	v_cndmask_b32_e32 v1, v1, v4, vcc
	v_mul_lo_u32 v4, v2, v1
	v_add_u32_e32 v2, v4, v2
	v_cmp_ne_u32_e32 vcc, v3, v2
	s_and_saveexec_b64 s[6:7], vcc
	s_xor_b64 s[6:7], exec, s[6:7]
	s_cbranch_execz .LBB0_683
	s_waitcnt lgkmcnt(0)
	v_mov_b32_e32 v0, 0x83100
	global_load_dword v0, v0, s[30:31] offset:1024 sc1
	s_add_u32 s12, s30, 0x83500
	s_addc_u32 s13, s31, 0
	s_waitcnt vmcnt(0)
	v_cmp_eq_u32_e32 vcc, v0, v1
	s_and_saveexec_b64 s[8:9], vcc
	s_cbranch_execz .LBB0_682
	s_add_u32 s10, s30, 0x80200
	s_addc_u32 s11, s31, 0
	s_mov_b32 s3, 1
	s_mov_b64 s[14:15], 0
	v_mov_b32_e32 v0, 0
	s_branch .LBB0_673

; __device__ __forceinline__ unsigned xb_ld(unsigned* p)              { return __hip_atomic_load(p, __ATOMIC_RELAXED, __HIP_MEMORY_SCOPE_AGENT); }
; #define XB_SPIN(cond, bar) do { unsigned _sp = 0; while (cond) { __builtin_amdgcn_s_sleep(1); \
;     if ((++_sp & 255u) == 0u) { if (xb_ld(&(bar)[XB_TMO])) break; if (_sp > XB_SPIN_CAP) { atomicAdd(&(bar)[XB_TMO], 1u); break; } } } } while (0)
; __device__ __forceinline__ void xcd_barrier(const XcdBarrier& b) {
;     ...
;         } else {
;             XB_SPIN(xb_ld(&bar[XB_XGEN(b.x)]) == gen, bar);
;             __builtin_amdgcn_fence(__ATOMIC_ACQUIRE, "agent");
;             asm volatile("s_waitcnt vmcnt(0)" ::: "memory");
.LBB0_682:
	s_or_b64 exec, exec, s[8:9]
	s_waitcnt vmcnt(0)
	s_waitcnt vmcnt(0)

; __device__ __forceinline__ unsigned xb_ld(unsigned* p)              { return __hip_atomic_load(p, __ATOMIC_RELAXED, __HIP_MEMORY_SCOPE_AGENT); }
; __device__ __forceinline__ unsigned xb_add(unsigned* p, unsigned v) { return __hip_atomic_fetch_add(p, v, __ATOMIC_RELAXED, __HIP_MEMORY_SCOPE_AGENT); }
; #define XB_SPIN(cond, bar) do { unsigned _sp = 0; while (cond) { __builtin_amdgcn_s_sleep(1); \
;     if ((++_sp & 255u) == 0u) { if (xb_ld(&(bar)[XB_TMO])) break; if (_sp > XB_SPIN_CAP) { atomicAdd(&(bar)[XB_TMO], 1u); break; } } } } while (0)
; __device__ __forceinline__ void xcd_barrier(const XcdBarrier& b) {
;     ...
;             const unsigned og = xb_add(&bar[XB_TOP], 1u);
;             const unsigned tg = og / nx;
;             if (og + 1u == (tg + 1u) * nx) xb_add(&bar[XB_TOPGEN], 1u);
;             else XB_SPIN(xb_ld(&bar[XB_TOPGEN]) == tg, bar);
;             __builtin_amdgcn_fence(__ATOMIC_ACQUIRE, "agent");
;             xb_add(&bar[XB_XGEN(b.x)], 1u);
;             asm volatile("s_waitcnt vmcnt(0)" ::: "memory");
.LBB0_700:
	s_or_b64 exec, exec, s[6:7]
	s_mov_b64 s[6:7], exec
	v_mbcnt_lo_u32_b32 v0, s6, 0
	v_mbcnt_hi_u32_b32 v0, s7, v0
	v_cmp_eq_u32_e32 vcc, 0, v0
	s_waitcnt vmcnt(0)
	s_and_saveexec_b64 s[8:9], vcc
	s_cbranch_execz .LBB0_702
	s_bcnt1_i32_b64 s3, s[6:7]
	v_mov_b32_e32 v0, 0x2000
	v_mov_b32_e32 v1, s3
	global_atomic_add v0, v1, s[4:5] offset:1024

; __device__ __forceinline__ unsigned xb_ld(unsigned* p)              { return __hip_atomic_load(p, __ATOMIC_RELAXED, __HIP_MEMORY_SCOPE_AGENT); }
; __device__ __forceinline__ unsigned xb_add(unsigned* p, unsigned v) { return __hip_atomic_fetch_add(p, v, __ATOMIC_RELAXED, __HIP_MEMORY_SCOPE_AGENT); }
; #define XB_SPIN(cond, bar) do { unsigned _sp = 0; while (cond) { __builtin_amdgcn_s_sleep(1); \
;     if ((++_sp & 255u) == 0u) { if (xb_ld(&(bar)[XB_TMO])) break; if (_sp > XB_SPIN_CAP) { atomicAdd(&(bar)[XB_TMO], 1u); break; } } } } while (0)
; __device__ __forceinline__ void xcd_barrier(const XcdBarrier& b) {
;     ...
;         unsigned nloc = b.st[0], nx = b.st[1];
;         if (nloc == 0u) { xcd_barrier_complete(bar, b.x, nloc, nx); b.st[0] = nloc; b.st[1] = nx; }
;         const unsigned old = xb_add(&bar[XB_XSUB(b.x)], 1u);
;         const unsigned gen = old / nloc;
;         if (old + 1u == (gen + 1u) * nloc) {
;             __builtin_amdgcn_fence(__ATOMIC_RELEASE, "agent");
;             asm volatile("s_waitcnt vmcnt(0)" ::: "memory");
;             const unsigned og = xb_add(&bar[XB_TOP], 1u);
;             const unsigned tg = og / nx;
;             if (og + 1u == (tg + 1u) * nx) xb_add(&bar[XB_TOPGEN], 1u);
;             else XB_SPIN(xb_ld(&bar[XB_TOPGEN]) == tg, bar);
;             __builtin_amdgcn_fence(__ATOMIC_ACQUIRE, "agent");
;             xb_add(&bar[XB_XGEN(b.x)], 1u);
;             asm volatile("s_waitcnt vmcnt(0)" ::: "memory");
;         } else {
;             XB_SPIN(xb_ld(&bar[XB_XGEN(b.x)]) == gen, bar);
;             __builtin_amdgcn_fence(__ATOMIC_ACQUIRE, "agent");
;             asm volatile("s_waitcnt vmcnt(0)" ::: "memory");
.LBB0_1506:
	s_or_b64 exec, exec, s[6:7]
	v_cvt_f32_u32_e32 v4, v2
	s_waitcnt vmcnt(0)
	buffer_inv sc1
	v_readfirstlane_b32 s4, v3
	v_sub_u32_e32 v3, 0, v2
	v_rcp_iflag_f32_e32 v4, v4
	v_add_u32_e32 v5, s4, v1
	v_mul_f32_e32 v4, 0x4f7ffffe, v4
	v_cvt_u32_f32_e32 v4, v4
	v_mul_lo_u32 v1, v3, v4
	v_mul_hi_u32 v1, v4, v1
	v_add_u32_e32 v1, v4, v1
	v_mul_hi_u32 v1, v5, v1
	v_mul_lo_u32 v3, v1, v2
	v_sub_u32_e32 v3, v5, v3
	v_add_u32_e32 v4, 1, v1
	v_cmp_ge_u32_e32 vcc, v3, v2
	s_nop 1
	v_cndmask_b32_e32 v1, v1, v4, vcc
	v_sub_u32_e32 v4, v3, v2
	v_cndmask_b32_e32 v3, v3, v4, vcc
	v_add_u32_e32 v4, 1, v1
	v_cmp_ge_u32_e32 vcc, v3, v2
	v_add_u32_e32 v3, 1, v5
	s_nop 0
	v_cndmask_b32_e32 v1, v1, v4, vcc
	v_mul_lo_u32 v4, v2, v1
	v_add_u32_e32 v2, v4, v2
	v_cmp_ne_u32_e32 vcc, v3, v2
	s_and_saveexec_b64 s[4:5], vcc
	s_xor_b64 s[4:5], exec, s[4:5]
	s_cbranch_execz .LBB0_1520
	s_waitcnt lgkmcnt(0)
	v_mov_b32_e32 v0, 0x83100
	global_load_dword v0, v0, s[30:31] offset:1024 sc1
	s_add_u32 s10, s30, 0x83500
	s_addc_u32 s11, s31, 0
	s_waitcnt vmcnt(0)
	v_cmp_eq_u32_e32 vcc, v0, v1
	s_and_saveexec_b64 s[6:7], vcc
	s_cbranch_execz .LBB0_1519
	s_add_u32 s8, s30, 0x80200
	s_addc_u32 s9, s31, 0
	s_mov_b32 s22, 1
	s_mov_b64 s[12:13], 0
	v_mov_b32_e32 v0, 0
	s_branch .LBB0_1510

; __device__ __forceinline__ unsigned xb_ld(unsigned* p)              { return __hip_atomic_load(p, __ATOMIC_RELAXED, __HIP_MEMORY_SCOPE_AGENT); }
; #define XB_SPIN(cond, bar) do { unsigned _sp = 0; while (cond) { __builtin_amdgcn_s_sleep(1); \
;     if ((++_sp & 255u) == 0u) { if (xb_ld(&(bar)[XB_TMO])) break; if (_sp > XB_SPIN_CAP) { atomicAdd(&(bar)[XB_TMO], 1u); break; } } } } while (0)
; __device__ __forceinline__ void xcd_barrier(const XcdBarrier& b) {
;     ...
;         } else {
;             XB_SPIN(xb_ld(&bar[XB_XGEN(b.x)]) == gen, bar);
;             __builtin_amdgcn_fence(__ATOMIC_ACQUIRE, "agent");
;             asm volatile("s_waitcnt vmcnt(0)" ::: "memory");
.LBB0_1519:
	s_or_b64 exec, exec, s[6:7]
	s_waitcnt vmcnt(0)
	s_waitcnt vmcnt(0)

; __device__ __forceinline__ unsigned xb_ld(unsigned* p)              { return __hip_atomic_load(p, __ATOMIC_RELAXED, __HIP_MEMORY_SCOPE_AGENT); }
; __device__ __forceinline__ unsigned xb_add(unsigned* p, unsigned v) { return __hip_atomic_fetch_add(p, v, __ATOMIC_RELAXED, __HIP_MEMORY_SCOPE_AGENT); }
; #define XB_SPIN(cond, bar) do { unsigned _sp = 0; while (cond) { __builtin_amdgcn_s_sleep(1); \
;     if ((++_sp & 255u) == 0u) { if (xb_ld(&(bar)[XB_TMO])) break; if (_sp > XB_SPIN_CAP) { atomicAdd(&(bar)[XB_TMO], 1u); break; } } } } while (0)
; __device__ __forceinline__ void xcd_barrier(const XcdBarrier& b) {
;     ...
;             const unsigned og = xb_add(&bar[XB_TOP], 1u);
;             const unsigned tg = og / nx;
;             if (og + 1u == (tg + 1u) * nx) xb_add(&bar[XB_TOPGEN], 1u);
;             else XB_SPIN(xb_ld(&bar[XB_TOPGEN]) == tg, bar);
;             __builtin_amdgcn_fence(__ATOMIC_ACQUIRE, "agent");
;             xb_add(&bar[XB_XGEN(b.x)], 1u);
;             asm volatile("s_waitcnt vmcnt(0)" ::: "memory");
.LBB0_1537:
	s_or_b64 exec, exec, s[4:5]
	s_mov_b64 s[4:5], exec
	v_mbcnt_lo_u32_b32 v0, s4, 0
	v_mbcnt_hi_u32_b32 v0, s5, v0
	v_cmp_eq_u32_e32 vcc, 0, v0
	s_waitcnt vmcnt(0)
	s_and_saveexec_b64 s[6:7], vcc
	s_cbranch_execz .LBB0_1539
	s_bcnt1_i32_b64 s4, s[4:5]
	v_mov_b32_e32 v0, 0x2000
	v_mov_b32_e32 v1, s4
	global_atomic_add v0, v1, s[2:3] offset:1024
